# MoBA gate: three returning list-append atomics issued back-to-back behind a single wait (was atomic-wait-store x3)
# baseline (speedup 1.0000x reference)
.LBB0_716:
	s_and_b64 s[0:1], s[36:37], exec
	s_cselect_b32 s6, s71, s70
	s_cmp_eq_u32 s6, 0
	s_cbranch_scc1 .LBB0_715
	v_mov_b32_e32 v6, v1
	s_lshl_b32 s1, s6, 8
	v_readfirstlane_b32 s0, v6
	s_ashr_i32 s0, s0, 1
	s_andn2_b32 s0, s0, 31
	v_lshlrev_b32_e32 v2, 4, v6
	v_and_b32_e32 v14, 31, v6
	s_add_i32 s0, s0, s1
	v_and_b32_e32 v10, 0xf0, v2
	v_mov_b32_e32 v11, v199
	v_bfe_u32 v92, v6, 5, 1
	v_lshl_add_u64 v[2:3], s[22:23], 0, v[10:11]
	v_ashrrev_i32_e32 v11, 4, v6
	v_add_u32_e32 v6, 0x200, v6
	v_or_b32_e32 v90, s0, v14
	v_ashrrev_i32_e32 v15, 4, v6
	v_ashrrev_i32_e32 v91, 31, v90
	v_lshlrev_b32_e32 v4, 7, v11
	v_lshlrev_b32_e32 v6, 7, v15
	v_lshlrev_b64 v[12:13], 11, v[90:91]
	v_ashrrev_i32_e32 v5, 31, v4
	v_ashrrev_i32_e32 v7, 31, v6
	v_lshl_add_u64 v[12:13], s[24:25], 0, v[12:13]
	v_lshlrev_b32_e32 v198, 4, v92
	v_lshl_add_u64 v[4:5], v[4:5], 1, v[2:3]
	v_lshl_add_u64 v[6:7], v[6:7], 1, v[2:3]
	v_lshl_add_u64 v[12:13], v[12:13], 0, v[198:199]
	global_load_dwordx4 v[2:5], v[4:5], off
	s_nop 0
	global_load_dwordx4 v[6:9], v[6:7], off
	s_nop 0
	global_load_dwordx4 v[18:21], v[12:13], off
	global_load_dwordx4 v[58:61], v[12:13], off offset:32
	global_load_dwordx4 v[54:57], v[12:13], off offset:64
	global_load_dwordx4 v[50:53], v[12:13], off offset:96
	global_load_dwordx4 v[46:49], v[12:13], off offset:128
	global_load_dwordx4 v[42:45], v[12:13], off offset:160
	global_load_dwordx4 v[38:41], v[12:13], off offset:192
	global_load_dwordx4 v[34:37], v[12:13], off offset:224
	v_mul_u32_u24_e32 v12, 0x110, v14
	v_add_u32_e32 v10, 0, v10
	v_add3_u32 v91, 0, v12, v198
	v_mad_u64_u32 v[12:13], s[0:1], v11, s59, v[10:11]
	v_mad_u64_u32 v[10:11], s[0:1], v15, s59, v[10:11]
	s_waitcnt vmcnt(0)
	ds_write_b128 v12, v[2:5]
	ds_write_b128 v10, v[6:9]
	s_waitcnt lgkmcnt(0)
	s_barrier
	s_waitcnt lgkmcnt(0)
	ds_read_b128 v[2:5], v91 offset:0
	ds_read_b128 v[22:25], v91 offset:0x2200
	ds_read_b128 v[26:29], v91 offset:32
	ds_read_b128 v[86:89], v91 offset:0x2220
	ds_read_b128 v[30:33], v91 offset:64
	ds_read_b128 v[82:85], v91 offset:0x2240
	s_setprio 1
	s_waitcnt lgkmcnt(4)
	ds_read_b128 v[62:65], v91 offset:0x60
	ds_read_b128 v[78:81], v91 offset:0x2260
	s_waitcnt lgkmcnt(4)
	s_nop 0
	v_mfma_f32_32x32x16_bf16 v[2:17], v[2:5], v[18:21], 0
	v_mfma_f32_32x32x16_bf16 v[2:17], v[26:29], v[58:61], v[2:17]
	ds_read_b128 v[26:29], v91 offset:0x80
	ds_read_b128 v[74:77], v91 offset:0x2280
	s_waitcnt lgkmcnt(4)
	s_nop 0
	v_mfma_f32_32x32x16_bf16 v[2:17], v[30:33], v[54:57], v[2:17]
	ds_read_b128 v[30:33], v91 offset:0xa0
	ds_read_b128 v[70:73], v91 offset:0x22a0
	s_waitcnt lgkmcnt(4)
	ds_read_b128 v[94:97], v91 offset:0xc0
	ds_read_b128 v[66:69], v91 offset:0x22c0
	s_waitcnt lgkmcnt(4)
	s_nop 0
	v_mfma_f32_32x32x16_bf16 v[2:17], v[62:65], v[50:53], v[2:17]
	v_mfma_f32_32x32x16_bf16 v[2:17], v[26:29], v[46:49], v[2:17]
	ds_read_b128 v[26:29], v91 offset:0xe0
	ds_read_b128 v[62:65], v91 offset:0x22e0
	s_waitcnt lgkmcnt(4)
	s_waitcnt lgkmcnt(2)
	s_nop 0
	s_waitcnt lgkmcnt(0)
	v_mfma_f32_32x32x16_bf16 v[2:17], v[30:33], v[42:45], v[2:17]
	v_mfma_f32_32x32x16_bf16 v[2:17], v[94:97], v[38:41], v[2:17]
	v_mfma_f32_32x32x16_bf16 v[2:17], v[26:29], v[34:37], v[2:17]
	s_setprio 0
	v_lshlrev_b32_e32 v91, 2, v92
	v_cmp_gt_u32_e32 vcc, s6, v91
	v_or_b32_e32 v27, 1, v91
	s_nop 7
	v_cndmask_b32_e32 v2, v211, v2, vcc
	v_cmp_lt_f32_e32 vcc, s60, v2
	v_max_f32_e32 v26, v2, v2
	v_max_f32_e32 v26, 0xff61b1e6, v26
	v_cndmask_b32_e32 v2, -1, v91, vcc
	v_cmp_gt_u32_e32 vcc, s6, v27
	s_nop 1
	v_cndmask_b32_e32 v3, v211, v3, vcc
	v_max_f32_e32 v28, v3, v3
	v_max_f32_e32 v28, 0xff61b1e6, v28
	v_cmp_gt_f32_e32 vcc, v3, v26
	v_cmp_lt_f32_e64 s[0:1], s60, v3
	s_nop 0
	v_cndmask_b32_e32 v28, v28, v26, vcc
	v_cndmask_b32_e64 v29, -1, v27, s[0:1]
	v_cndmask_b32_e32 v3, v26, v3, vcc
	v_or_b32_e32 v26, 2, v91
	v_cndmask_b32_e32 v27, v2, v27, vcc
	v_cndmask_b32_e32 v2, v29, v2, vcc
	v_cmp_gt_u32_e32 vcc, s6, v26
	s_nop 1
	v_cndmask_b32_e32 v4, v211, v4, vcc
	v_max_f32_e32 v29, v4, v4
	v_max_f32_e32 v29, 0xff61b1e6, v29
	v_cmp_gt_f32_e32 vcc, v4, v28
	v_cmp_lt_f32_e64 s[0:1], s60, v4
	s_nop 0
	v_cndmask_b32_e32 v29, v29, v28, vcc
	v_cndmask_b32_e64 v30, -1, v26, s[0:1]
	v_cndmask_b32_e32 v28, v28, v4, vcc
	v_cmp_gt_f32_e64 s[0:1], v4, v3
	v_cndmask_b32_e32 v30, v30, v2, vcc
	v_cndmask_b32_e32 v2, v2, v26, vcc
	v_cndmask_b32_e64 v28, v28, v3, s[0:1]
	v_cndmask_b32_e64 v3, v3, v4, s[0:1]
	v_or_b32_e32 v4, 3, v91
	v_cmp_gt_u32_e32 vcc, s6, v4
	v_cndmask_b32_e64 v26, v27, v26, s[0:1]
	v_cndmask_b32_e64 v2, v2, v27, s[0:1]
	v_cndmask_b32_e32 v5, v211, v5, vcc
	v_cmp_gt_f32_e32 vcc, v5, v29
	v_cmp_gt_f32_e64 s[0:1], v5, v28
	s_nop 0
	v_cndmask_b32_e32 v27, v29, v5, vcc
	v_cndmask_b32_e64 v27, v27, v28, s[0:1]
	v_cndmask_b32_e32 v29, v30, v4, vcc
	v_cndmask_b32_e64 v28, v28, v5, s[0:1]
	v_cmp_gt_f32_e32 vcc, v5, v3
	v_cndmask_b32_e64 v29, v29, v2, s[0:1]
	v_cndmask_b32_e64 v2, v2, v4, s[0:1]
	v_cndmask_b32_e32 v28, v28, v3, vcc
	v_cndmask_b32_e32 v3, v3, v5, vcc
	v_or_b32_e32 v5, 8, v91
	v_cndmask_b32_e32 v4, v26, v4, vcc
	v_cndmask_b32_e32 v2, v2, v26, vcc
	v_cmp_gt_u32_e32 vcc, s6, v5
	s_nop 1
	v_cndmask_b32_e32 v6, v211, v6, vcc
	v_cmp_gt_f32_e32 vcc, v6, v27
	v_cmp_gt_f32_e64 s[0:1], v6, v28
	s_nop 0
	v_cndmask_b32_e32 v26, v27, v6, vcc
	v_cndmask_b32_e32 v27, v29, v5, vcc
	v_cndmask_b32_e64 v27, v27, v2, s[0:1]
	v_cmp_gt_f32_e32 vcc, v6, v3
	v_cndmask_b32_e64 v2, v2, v5, s[0:1]
	v_cndmask_b32_e64 v26, v26, v28, s[0:1]
	v_cndmask_b32_e64 v28, v28, v6, s[0:1]
	v_cndmask_b32_e32 v5, v4, v5, vcc
	v_cndmask_b32_e32 v2, v2, v4, vcc
	v_or_b32_e32 v4, 9, v91
	v_cndmask_b32_e32 v28, v28, v3, vcc
	v_cndmask_b32_e32 v3, v3, v6, vcc
	v_cmp_gt_u32_e32 vcc, s6, v4
	s_nop 1
	v_cndmask_b32_e32 v6, v211, v7, vcc
	v_cmp_gt_f32_e32 vcc, v6, v26
	v_cmp_gt_f32_e64 s[0:1], v6, v28
	s_nop 0
	v_cndmask_b32_e32 v7, v26, v6, vcc
	v_cndmask_b32_e32 v26, v27, v4, vcc
	v_cndmask_b32_e64 v26, v26, v2, s[0:1]
	v_cmp_gt_f32_e32 vcc, v6, v3
	v_cndmask_b32_e64 v2, v2, v4, s[0:1]
	v_cndmask_b32_e64 v27, v28, v6, s[0:1]
	v_cndmask_b32_e32 v4, v5, v4, vcc
	v_cndmask_b32_e32 v2, v2, v5, vcc
	v_or_b32_e32 v5, 10, v91
	v_cndmask_b32_e32 v27, v27, v3, vcc
	v_cndmask_b32_e32 v3, v3, v6, vcc
	v_cmp_gt_u32_e32 vcc, s6, v5
	v_cndmask_b32_e64 v7, v7, v28, s[0:1]
	s_nop 0
	v_cndmask_b32_e32 v6, v211, v8, vcc
	v_cmp_gt_f32_e32 vcc, v6, v7
	v_cmp_gt_f32_e64 s[0:1], v6, v27
	s_nop 0
	v_cndmask_b32_e32 v8, v26, v5, vcc
	v_cndmask_b32_e32 v7, v7, v6, vcc
	v_cndmask_b32_e64 v8, v8, v2, s[0:1]
	v_cmp_gt_f32_e32 vcc, v6, v3
	v_cndmask_b32_e64 v2, v2, v5, s[0:1]
	v_cndmask_b32_e64 v26, v27, v6, s[0:1]
	v_cndmask_b32_e32 v5, v4, v5, vcc
	v_cndmask_b32_e32 v2, v2, v4, vcc
	v_or_b32_e32 v4, 11, v91
	v_cndmask_b32_e32 v26, v26, v3, vcc
	v_cndmask_b32_e32 v3, v3, v6, vcc
	v_cmp_gt_u32_e32 vcc, s6, v4
	v_cndmask_b32_e64 v7, v7, v27, s[0:1]
	s_nop 0
	v_cndmask_b32_e32 v6, v211, v9, vcc
	v_cmp_gt_f32_e32 vcc, v6, v7
	v_cmp_gt_f32_e64 s[0:1], v6, v26
	s_nop 0
	v_cndmask_b32_e32 v7, v7, v6, vcc
	v_cndmask_b32_e64 v7, v7, v26, s[0:1]
	v_cndmask_b32_e64 v9, v26, v6, s[0:1]
	v_mfma_f32_32x32x16_bf16 v[18:33], v[22:25], v[18:21], 0
	v_cndmask_b32_e32 v8, v8, v4, vcc
	v_cndmask_b32_e64 v8, v8, v2, s[0:1]
	v_cmp_gt_f32_e32 vcc, v6, v3
	v_cndmask_b32_e64 v2, v2, v4, s[0:1]
	s_nop 0
	v_cndmask_b32_e32 v4, v5, v4, vcc
	v_cndmask_b32_e32 v2, v2, v5, vcc
	v_mfma_f32_32x32x16_bf16 v[18:33], v[86:89], v[58:61], v[18:33]
	v_or_b32_e32 v5, 16, v91
	v_cndmask_b32_e32 v9, v9, v3, vcc
	v_cndmask_b32_e32 v3, v3, v6, vcc
	v_cmp_gt_u32_e32 vcc, s6, v5
	s_nop 1
	v_cndmask_b32_e32 v6, v211, v10, vcc
	v_mfma_f32_32x32x16_bf16 v[18:33], v[82:85], v[54:57], v[18:33]
	v_cmp_gt_f32_e32 vcc, v6, v7
	v_cmp_gt_f32_e64 s[0:1], v6, v9
	s_nop 0
	v_cndmask_b32_e32 v8, v8, v5, vcc
	v_cndmask_b32_e32 v7, v7, v6, vcc
	v_cndmask_b32_e64 v8, v8, v2, s[0:1]
	v_cmp_gt_f32_e32 vcc, v6, v3
	v_cndmask_b32_e64 v2, v2, v5, s[0:1]
	v_cndmask_b32_e64 v7, v7, v9, s[0:1]
	v_cndmask_b32_e64 v9, v9, v6, s[0:1]
	v_cndmask_b32_e32 v5, v4, v5, vcc
	v_cndmask_b32_e32 v2, v2, v4, vcc
	v_or_b32_e32 v4, 17, v91
	v_cndmask_b32_e32 v9, v9, v3, vcc
	v_cndmask_b32_e32 v3, v3, v6, vcc
	v_cmp_gt_u32_e32 vcc, s6, v4
	v_mfma_f32_32x32x16_bf16 v[18:33], v[78:81], v[50:53], v[18:33]
	s_nop 0
	v_cndmask_b32_e32 v6, v211, v11, vcc
	v_cmp_gt_f32_e32 vcc, v6, v7
	v_cmp_gt_f32_e64 s[0:1], v6, v9
	v_or_b32_e32 v11, 59, v91
	v_cndmask_b32_e32 v8, v8, v4, vcc
	v_cndmask_b32_e32 v7, v7, v6, vcc
	v_cndmask_b32_e64 v8, v8, v2, s[0:1]
	v_cmp_gt_f32_e32 vcc, v6, v3
	v_cndmask_b32_e64 v2, v2, v4, s[0:1]
	v_cndmask_b32_e64 v7, v7, v9, s[0:1]
	v_cndmask_b32_e64 v9, v9, v6, s[0:1]
	v_cndmask_b32_e32 v4, v5, v4, vcc
	v_cndmask_b32_e32 v2, v2, v5, vcc
	v_or_b32_e32 v5, 18, v91
	v_cndmask_b32_e32 v9, v9, v3, vcc
	v_cndmask_b32_e32 v3, v3, v6, vcc
	v_cmp_gt_u32_e32 vcc, s6, v5
	v_mfma_f32_32x32x16_bf16 v[18:33], v[74:77], v[46:49], v[18:33]
	s_nop 0
	v_cndmask_b32_e32 v6, v211, v12, vcc
	v_cmp_gt_f32_e32 vcc, v6, v7
	v_cmp_gt_f32_e64 s[0:1], v6, v9
	s_nop 0
	v_cndmask_b32_e32 v8, v8, v5, vcc
	v_cndmask_b32_e32 v7, v7, v6, vcc
	v_cndmask_b32_e64 v8, v8, v2, s[0:1]
	v_cmp_gt_f32_e32 vcc, v6, v3
	v_cndmask_b32_e64 v2, v2, v5, s[0:1]
	v_cndmask_b32_e64 v7, v7, v9, s[0:1]
	v_cndmask_b32_e64 v9, v9, v6, s[0:1]
	v_cndmask_b32_e32 v5, v4, v5, vcc
	v_cndmask_b32_e32 v2, v2, v4, vcc
	v_or_b32_e32 v4, 19, v91
	v_cndmask_b32_e32 v9, v9, v3, vcc
	v_cndmask_b32_e32 v3, v3, v6, vcc
	v_cmp_gt_u32_e32 vcc, s6, v4
	v_mfma_f32_32x32x16_bf16 v[18:33], v[70:73], v[42:45], v[18:33]
	s_nop 0
	v_cndmask_b32_e32 v6, v211, v13, vcc
	v_cmp_gt_f32_e32 vcc, v6, v7
	v_cmp_gt_f32_e64 s[0:1], v6, v9
	s_nop 0
	v_cndmask_b32_e32 v8, v8, v4, vcc
	v_cndmask_b32_e32 v7, v7, v6, vcc
	v_cndmask_b32_e64 v8, v8, v2, s[0:1]
	v_cmp_gt_f32_e32 vcc, v6, v3
	v_cndmask_b32_e64 v2, v2, v4, s[0:1]
	v_cndmask_b32_e64 v7, v7, v9, s[0:1]
	v_cndmask_b32_e64 v9, v9, v6, s[0:1]
	v_cndmask_b32_e32 v4, v5, v4, vcc
	v_cndmask_b32_e32 v2, v2, v5, vcc
	v_or_b32_e32 v5, 24, v91
	v_cndmask_b32_e32 v9, v9, v3, vcc
	v_cndmask_b32_e32 v3, v3, v6, vcc
	v_cmp_gt_u32_e32 vcc, s6, v5
	v_mfma_f32_32x32x16_bf16 v[18:33], v[66:69], v[38:41], v[18:33]
	s_nop 0
	v_cndmask_b32_e32 v6, v211, v14, vcc
	v_cmp_gt_f32_e32 vcc, v6, v7
	v_cmp_gt_f32_e64 s[0:1], v6, v9
	s_nop 0
	v_cndmask_b32_e32 v8, v8, v5, vcc
	v_cndmask_b32_e32 v7, v7, v6, vcc
	v_cndmask_b32_e64 v8, v8, v2, s[0:1]
	v_cmp_gt_f32_e32 vcc, v6, v3
	v_cndmask_b32_e64 v2, v2, v5, s[0:1]
	v_cndmask_b32_e64 v7, v7, v9, s[0:1]
	v_cndmask_b32_e64 v9, v9, v6, s[0:1]
	v_cndmask_b32_e32 v5, v4, v5, vcc
	v_cndmask_b32_e32 v2, v2, v4, vcc
	v_or_b32_e32 v4, 25, v91
	v_cndmask_b32_e32 v9, v9, v3, vcc
	v_cndmask_b32_e32 v3, v3, v6, vcc
	v_cmp_gt_u32_e32 vcc, s6, v4
	v_mfma_f32_32x32x16_bf16 v[18:33], v[62:65], v[34:37], v[18:33]
	s_nop 0
	v_cndmask_b32_e32 v6, v211, v15, vcc
	v_cmp_gt_f32_e32 vcc, v6, v7
	v_cmp_gt_f32_e64 s[0:1], v6, v9
	s_nop 0
	v_cndmask_b32_e32 v8, v8, v4, vcc
	v_cndmask_b32_e32 v7, v7, v6, vcc
	v_cndmask_b32_e64 v8, v8, v2, s[0:1]
	v_cmp_gt_f32_e32 vcc, v6, v3
	v_cndmask_b32_e64 v2, v2, v4, s[0:1]
	v_cndmask_b32_e64 v7, v7, v9, s[0:1]
	v_cndmask_b32_e64 v9, v9, v6, s[0:1]
	v_cndmask_b32_e32 v4, v5, v4, vcc
	v_cndmask_b32_e32 v2, v2, v5, vcc
	v_or_b32_e32 v5, 26, v91
	v_cndmask_b32_e32 v9, v9, v3, vcc
	v_cndmask_b32_e32 v3, v3, v6, vcc
	v_cmp_gt_u32_e32 vcc, s6, v5
	s_nop 1
	v_cndmask_b32_e32 v6, v211, v16, vcc
	v_cmp_gt_f32_e32 vcc, v6, v7
	v_cmp_gt_f32_e64 s[0:1], v6, v9
	s_nop 0
	v_cndmask_b32_e32 v8, v8, v5, vcc
	v_cndmask_b32_e32 v7, v7, v6, vcc
	v_cndmask_b32_e64 v8, v8, v2, s[0:1]
	v_cmp_gt_f32_e32 vcc, v6, v3
	v_cndmask_b32_e64 v2, v2, v5, s[0:1]
	v_cndmask_b32_e64 v7, v7, v9, s[0:1]
	v_cndmask_b32_e64 v9, v9, v6, s[0:1]
	v_cndmask_b32_e32 v5, v4, v5, vcc
	v_cndmask_b32_e32 v2, v2, v4, vcc
	v_or_b32_e32 v4, 27, v91
	v_cndmask_b32_e32 v9, v9, v3, vcc
	v_cndmask_b32_e32 v3, v3, v6, vcc
	v_cmp_gt_u32_e32 vcc, s6, v4
	s_nop 1
	v_cndmask_b32_e32 v6, v211, v17, vcc
	v_cmp_gt_f32_e32 vcc, v6, v7
	v_cmp_gt_f32_e64 s[0:1], v6, v9
	s_nop 0
	v_cndmask_b32_e32 v8, v8, v4, vcc
	v_cndmask_b32_e32 v7, v7, v6, vcc
	v_cndmask_b32_e64 v8, v8, v2, s[0:1]
	v_cmp_gt_f32_e32 vcc, v6, v3
	v_cndmask_b32_e64 v2, v2, v4, s[0:1]
	v_cndmask_b32_e64 v7, v7, v9, s[0:1]
	v_cndmask_b32_e64 v9, v9, v6, s[0:1]
	v_cndmask_b32_e32 v4, v5, v4, vcc
	v_cndmask_b32_e32 v2, v2, v5, vcc
	v_or_b32_e32 v5, 32, v91
	v_cndmask_b32_e32 v9, v9, v3, vcc
	v_cndmask_b32_e32 v3, v3, v6, vcc
	v_cmp_gt_u32_e32 vcc, s6, v5
	s_nop 1
	v_cndmask_b32_e32 v6, v211, v18, vcc
	v_cmp_gt_f32_e32 vcc, v6, v7
	v_cmp_gt_f32_e64 s[0:1], v6, v9
	s_nop 0
	v_cndmask_b32_e32 v8, v8, v5, vcc
	v_cndmask_b32_e32 v7, v7, v6, vcc
	v_cndmask_b32_e64 v8, v8, v2, s[0:1]
	v_cmp_gt_f32_e32 vcc, v6, v3
	v_cndmask_b32_e64 v2, v2, v5, s[0:1]
	v_cndmask_b32_e64 v7, v7, v9, s[0:1]
	v_cndmask_b32_e64 v9, v9, v6, s[0:1]
	v_cndmask_b32_e32 v5, v4, v5, vcc
	v_cndmask_b32_e32 v2, v2, v4, vcc
	v_or_b32_e32 v4, 33, v91
	v_cndmask_b32_e32 v9, v9, v3, vcc
	v_cndmask_b32_e32 v3, v3, v6, vcc
	v_cmp_gt_u32_e32 vcc, s6, v4
	s_nop 1
	v_cndmask_b32_e32 v6, v211, v19, vcc
	v_cmp_gt_f32_e32 vcc, v6, v7
	v_cmp_gt_f32_e64 s[0:1], v6, v9
	s_nop 0
	v_cndmask_b32_e32 v8, v8, v4, vcc
	v_cndmask_b32_e32 v7, v7, v6, vcc
	v_cndmask_b32_e64 v8, v8, v2, s[0:1]
	v_cmp_gt_f32_e32 vcc, v6, v3
	v_cndmask_b32_e64 v2, v2, v4, s[0:1]
	v_cndmask_b32_e64 v7, v7, v9, s[0:1]
	v_cndmask_b32_e64 v9, v9, v6, s[0:1]
	v_cndmask_b32_e32 v4, v5, v4, vcc
	v_cndmask_b32_e32 v2, v2, v5, vcc
	v_or_b32_e32 v5, 34, v91
	v_cndmask_b32_e32 v9, v9, v3, vcc
	v_cndmask_b32_e32 v3, v3, v6, vcc
	v_cmp_gt_u32_e32 vcc, s6, v5
	s_nop 1
	v_cndmask_b32_e32 v6, v211, v20, vcc
	v_cmp_gt_f32_e32 vcc, v6, v7
	v_cmp_gt_f32_e64 s[0:1], v6, v9
	s_nop 0
	v_cndmask_b32_e32 v8, v8, v5, vcc
	v_cndmask_b32_e32 v7, v7, v6, vcc
	v_cndmask_b32_e64 v8, v8, v2, s[0:1]
	v_cmp_gt_f32_e32 vcc, v6, v3
	v_cndmask_b32_e64 v2, v2, v5, s[0:1]
	v_cndmask_b32_e64 v7, v7, v9, s[0:1]
	v_cndmask_b32_e64 v9, v9, v6, s[0:1]
	v_cndmask_b32_e32 v5, v4, v5, vcc
	v_cndmask_b32_e32 v2, v2, v4, vcc
	v_or_b32_e32 v4, 35, v91
	v_cndmask_b32_e32 v9, v9, v3, vcc
	v_cndmask_b32_e32 v3, v3, v6, vcc
	v_cmp_gt_u32_e32 vcc, s6, v4
	s_nop 1
	v_cndmask_b32_e32 v6, v211, v21, vcc
	v_cmp_gt_f32_e32 vcc, v6, v7
	v_cmp_gt_f32_e64 s[0:1], v6, v9
	s_nop 0
	v_cndmask_b32_e32 v8, v8, v4, vcc
	v_cndmask_b32_e32 v7, v7, v6, vcc
	v_cndmask_b32_e64 v8, v8, v2, s[0:1]
	v_cmp_gt_f32_e32 vcc, v6, v3
	v_cndmask_b32_e64 v2, v2, v4, s[0:1]
	v_cndmask_b32_e64 v7, v7, v9, s[0:1]
	v_cndmask_b32_e64 v9, v9, v6, s[0:1]
	v_cndmask_b32_e32 v4, v5, v4, vcc
	v_cndmask_b32_e32 v2, v2, v5, vcc
	v_or_b32_e32 v5, 40, v91
	v_cndmask_b32_e32 v9, v9, v3, vcc
	v_cndmask_b32_e32 v3, v3, v6, vcc
	v_cmp_gt_u32_e32 vcc, s6, v5
	s_nop 1
	v_cndmask_b32_e32 v6, v211, v22, vcc
	v_cmp_gt_f32_e32 vcc, v6, v7
	v_cmp_gt_f32_e64 s[0:1], v6, v9
	s_nop 0
	v_cndmask_b32_e32 v8, v8, v5, vcc
	v_cndmask_b32_e32 v7, v7, v6, vcc
	v_cndmask_b32_e64 v8, v8, v2, s[0:1]
	v_cmp_gt_f32_e32 vcc, v6, v3
	v_cndmask_b32_e64 v2, v2, v5, s[0:1]
	v_cndmask_b32_e64 v7, v7, v9, s[0:1]
	v_cndmask_b32_e64 v9, v9, v6, s[0:1]
	v_cndmask_b32_e32 v5, v4, v5, vcc
	v_cndmask_b32_e32 v2, v2, v4, vcc
	v_or_b32_e32 v4, 41, v91
	v_cndmask_b32_e32 v9, v9, v3, vcc
	v_cndmask_b32_e32 v3, v3, v6, vcc
	v_cmp_gt_u32_e32 vcc, s6, v4
	s_nop 1
	v_cndmask_b32_e32 v6, v211, v23, vcc
	v_cmp_gt_f32_e32 vcc, v6, v7
	v_cmp_gt_f32_e64 s[0:1], v6, v9
	s_nop 0
	v_cndmask_b32_e32 v8, v8, v4, vcc
	v_cndmask_b32_e32 v7, v7, v6, vcc
	v_cndmask_b32_e64 v8, v8, v2, s[0:1]
	v_cmp_gt_f32_e32 vcc, v6, v3
	v_cndmask_b32_e64 v2, v2, v4, s[0:1]
	v_cndmask_b32_e64 v7, v7, v9, s[0:1]
	v_cndmask_b32_e64 v9, v9, v6, s[0:1]
	v_cndmask_b32_e32 v4, v5, v4, vcc
	v_cndmask_b32_e32 v2, v2, v5, vcc
	v_or_b32_e32 v5, 42, v91
	v_cndmask_b32_e32 v9, v9, v3, vcc
	v_cndmask_b32_e32 v3, v3, v6, vcc
	v_cmp_gt_u32_e32 vcc, s6, v5
	s_nop 1
	v_cndmask_b32_e32 v6, v211, v24, vcc
	v_cmp_gt_f32_e32 vcc, v6, v7
	v_cmp_gt_f32_e64 s[0:1], v6, v9
	s_nop 0
	v_cndmask_b32_e32 v8, v8, v5, vcc
	v_cndmask_b32_e32 v7, v7, v6, vcc
	v_cndmask_b32_e64 v8, v8, v2, s[0:1]
	v_cmp_gt_f32_e32 vcc, v6, v3
	v_cndmask_b32_e64 v2, v2, v5, s[0:1]
	v_cndmask_b32_e64 v7, v7, v9, s[0:1]
	v_cndmask_b32_e64 v9, v9, v6, s[0:1]
	v_cndmask_b32_e32 v5, v4, v5, vcc
	v_cndmask_b32_e32 v2, v2, v4, vcc
	v_or_b32_e32 v4, 43, v91
	v_cndmask_b32_e32 v9, v9, v3, vcc
	v_cndmask_b32_e32 v3, v3, v6, vcc
	v_cmp_gt_u32_e32 vcc, s6, v4
	s_nop 1
	v_cndmask_b32_e32 v6, v211, v25, vcc
	v_cmp_gt_f32_e32 vcc, v6, v7
	v_cmp_gt_f32_e64 s[0:1], v6, v9
	s_nop 0
	v_cndmask_b32_e32 v8, v8, v4, vcc
	v_cndmask_b32_e32 v7, v7, v6, vcc
	v_cndmask_b32_e64 v8, v8, v2, s[0:1]
	v_cmp_gt_f32_e32 vcc, v6, v3
	v_cndmask_b32_e64 v2, v2, v4, s[0:1]
	v_cndmask_b32_e64 v7, v7, v9, s[0:1]
	v_cndmask_b32_e64 v9, v9, v6, s[0:1]
	v_cndmask_b32_e32 v4, v5, v4, vcc
	v_cndmask_b32_e32 v2, v2, v5, vcc
	v_or_b32_e32 v5, 48, v91
	v_cndmask_b32_e32 v9, v9, v3, vcc
	v_cndmask_b32_e32 v3, v3, v6, vcc
	v_cmp_gt_u32_e32 vcc, s6, v5
	s_nop 1
	v_cndmask_b32_e32 v6, v211, v26, vcc
	v_cmp_gt_f32_e32 vcc, v6, v7
	v_cmp_gt_f32_e64 s[0:1], v6, v9
	s_nop 0
	v_cndmask_b32_e32 v8, v8, v5, vcc
	v_cndmask_b32_e32 v7, v7, v6, vcc
	v_cndmask_b32_e64 v8, v8, v2, s[0:1]
	v_cmp_gt_f32_e32 vcc, v6, v3
	v_cndmask_b32_e64 v2, v2, v5, s[0:1]
	v_cndmask_b32_e64 v7, v7, v9, s[0:1]
	v_cndmask_b32_e64 v9, v9, v6, s[0:1]
	v_cndmask_b32_e32 v5, v4, v5, vcc
	v_cndmask_b32_e32 v2, v2, v4, vcc
	v_or_b32_e32 v4, 49, v91
	v_cndmask_b32_e32 v9, v9, v3, vcc
	v_cndmask_b32_e32 v3, v3, v6, vcc
	v_cmp_gt_u32_e32 vcc, s6, v4
	s_nop 1
	v_cndmask_b32_e32 v6, v211, v27, vcc
	v_cmp_gt_f32_e32 vcc, v6, v7
	v_cmp_gt_f32_e64 s[0:1], v6, v9
	s_nop 0
	v_cndmask_b32_e32 v8, v8, v4, vcc
	v_cndmask_b32_e32 v7, v7, v6, vcc
	v_cndmask_b32_e64 v8, v8, v2, s[0:1]
	v_cmp_gt_f32_e32 vcc, v6, v3
	v_cndmask_b32_e64 v2, v2, v4, s[0:1]
	v_cndmask_b32_e64 v7, v7, v9, s[0:1]
	v_cndmask_b32_e64 v9, v9, v6, s[0:1]
	v_cndmask_b32_e32 v4, v5, v4, vcc
	v_cndmask_b32_e32 v2, v2, v5, vcc
	v_or_b32_e32 v5, 50, v91
	v_cndmask_b32_e32 v9, v9, v3, vcc
	v_cndmask_b32_e32 v3, v3, v6, vcc
	v_cmp_gt_u32_e32 vcc, s6, v5
	s_nop 1
	v_cndmask_b32_e32 v6, v211, v28, vcc
	v_cmp_gt_f32_e32 vcc, v6, v7
	v_cmp_gt_f32_e64 s[0:1], v6, v9
	s_nop 0
	v_cndmask_b32_e32 v8, v8, v5, vcc
	v_cndmask_b32_e32 v7, v7, v6, vcc
	v_cndmask_b32_e64 v8, v8, v2, s[0:1]
	v_cmp_gt_f32_e32 vcc, v6, v3
	v_cndmask_b32_e64 v2, v2, v5, s[0:1]
	v_cndmask_b32_e64 v7, v7, v9, s[0:1]
	v_cndmask_b32_e64 v9, v9, v6, s[0:1]
	v_cndmask_b32_e32 v5, v4, v5, vcc
	v_cndmask_b32_e32 v2, v2, v4, vcc
	v_or_b32_e32 v4, 51, v91
	v_cndmask_b32_e32 v9, v9, v3, vcc
	v_cndmask_b32_e32 v3, v3, v6, vcc
	v_cmp_gt_u32_e32 vcc, s6, v4
	s_nop 1
	v_cndmask_b32_e32 v6, v211, v29, vcc
	v_cmp_gt_f32_e32 vcc, v6, v7
	v_cmp_gt_f32_e64 s[0:1], v6, v9
	s_nop 0
	v_cndmask_b32_e32 v8, v8, v4, vcc
	v_cndmask_b32_e32 v7, v7, v6, vcc
	v_cndmask_b32_e64 v8, v8, v2, s[0:1]
	v_cmp_gt_f32_e32 vcc, v6, v3
	v_cndmask_b32_e64 v2, v2, v4, s[0:1]
	v_cndmask_b32_e64 v7, v7, v9, s[0:1]
	v_cndmask_b32_e64 v9, v9, v6, s[0:1]
	v_cndmask_b32_e32 v4, v5, v4, vcc
	v_cndmask_b32_e32 v2, v2, v5, vcc
	v_or_b32_e32 v5, 56, v91
	v_cndmask_b32_e32 v9, v9, v3, vcc
	v_cndmask_b32_e32 v3, v3, v6, vcc
	v_cmp_gt_u32_e32 vcc, s6, v5
	s_nop 1
	v_cndmask_b32_e32 v6, v211, v30, vcc
	v_cmp_gt_f32_e32 vcc, v6, v7
	v_cmp_gt_f32_e64 s[0:1], v6, v9
	s_nop 0
	v_cndmask_b32_e32 v8, v8, v5, vcc
	v_cndmask_b32_e32 v7, v7, v6, vcc
	v_cndmask_b32_e64 v8, v8, v2, s[0:1]
	v_cmp_gt_f32_e32 vcc, v6, v3
	v_cndmask_b32_e64 v2, v2, v5, s[0:1]
	v_cndmask_b32_e64 v7, v7, v9, s[0:1]
	v_cndmask_b32_e64 v9, v9, v6, s[0:1]
	v_cndmask_b32_e32 v5, v4, v5, vcc
	v_cndmask_b32_e32 v2, v2, v4, vcc
	v_or_b32_e32 v4, 57, v91
	v_cndmask_b32_e32 v9, v9, v3, vcc
	v_cndmask_b32_e32 v3, v3, v6, vcc
	v_cmp_gt_u32_e32 vcc, s6, v4
	s_nop 1
	v_cndmask_b32_e32 v6, v211, v31, vcc
	v_cmp_gt_f32_e32 vcc, v6, v7
	v_cmp_gt_f32_e64 s[0:1], v6, v9
	s_nop 0
	v_cndmask_b32_e32 v8, v8, v4, vcc
	v_cndmask_b32_e32 v7, v7, v6, vcc
	v_cndmask_b32_e64 v8, v8, v2, s[0:1]
	v_cmp_gt_f32_e32 vcc, v6, v3
	v_cndmask_b32_e64 v2, v2, v4, s[0:1]
	v_cndmask_b32_e64 v7, v7, v9, s[0:1]
	v_cndmask_b32_e64 v9, v9, v6, s[0:1]
	v_cndmask_b32_e32 v4, v5, v4, vcc
	v_cndmask_b32_e32 v2, v2, v5, vcc
	v_or_b32_e32 v5, 58, v91
	v_cndmask_b32_e32 v9, v9, v3, vcc
	v_cndmask_b32_e32 v3, v3, v6, vcc
	v_cmp_gt_u32_e32 vcc, s6, v5
	s_nop 1
	v_cndmask_b32_e32 v6, v211, v32, vcc
	v_cmp_gt_f32_e32 vcc, v6, v7
	v_cmp_gt_f32_e64 s[0:1], v6, v9
	s_nop 0
	v_cndmask_b32_e32 v7, v7, v6, vcc
	v_cndmask_b32_e32 v8, v8, v5, vcc
	v_cndmask_b32_e64 v7, v7, v9, s[0:1]
	v_cndmask_b32_e64 v8, v8, v2, s[0:1]
	v_cndmask_b32_e64 v9, v9, v6, s[0:1]
	v_cmp_gt_f32_e32 vcc, v6, v3
	v_cndmask_b32_e64 v2, v2, v5, s[0:1]
	s_nop 0
	v_cndmask_b32_e32 v9, v9, v3, vcc
	v_cndmask_b32_e32 v5, v4, v5, vcc
	v_cndmask_b32_e32 v6, v3, v6, vcc
	v_cndmask_b32_e32 v10, v2, v4, vcc
	v_cmp_gt_u32_e32 vcc, s6, v11
	s_nop 1
	v_cndmask_b32_e32 v13, v211, v33, vcc
	v_cmp_gt_f32_e32 vcc, v13, v7
	v_cmp_gt_f32_e64 s[0:1], v13, v9
	s_nop 0
	v_cndmask_b32_e32 v2, v7, v13, vcc
	v_cndmask_b32_e32 v3, v8, v11, vcc
	v_cndmask_b32_e64 v4, v9, v13, s[0:1]
	v_cmp_gt_f32_e32 vcc, v13, v6
	v_cndmask_b32_e64 v7, v10, v11, s[0:1]
	v_cndmask_b32_e64 v2, v2, v9, s[0:1]
	v_cndmask_b32_e32 v4, v4, v6, vcc
	v_cndmask_b32_e32 v12, v5, v11, vcc
	v_cndmask_b32_e32 v13, v6, v13, vcc
	v_cndmask_b32_e32 v5, v7, v5, vcc
	v_cmp_lt_i32_e32 vcc, v212, v213
	v_cndmask_b32_e64 v3, v3, v10, s[0:1]
	s_nop 0
	v_cndmask_b32_e32 v6, v210, v212, vcc
	v_lshlrev_b32_e32 v7, 2, v6
	ds_bpermute_b32 v10, v7, v13
	ds_bpermute_b32 v8, v7, v4
	ds_bpermute_b32 v6, v7, v2
	ds_bpermute_b32 v11, v7, v12
	ds_bpermute_b32 v9, v7, v5
	ds_bpermute_b32 v7, v7, v3
	v_cmp_eq_u32_e32 vcc, 0, v92
	s_and_saveexec_b64 s[38:39], vcc
	s_cbranch_execz .LBB0_714
	s_waitcnt lgkmcnt(5)
	v_cmp_lt_f32_e64 s[0:1], v13, v10
	s_nop 1
	v_cndmask_b32_e64 v16, v13, v10, s[0:1]
	s_waitcnt lgkmcnt(4)
	v_cmp_lt_f32_e64 s[6:7], v16, v8
	s_waitcnt lgkmcnt(2)
	v_cndmask_b32_e64 v14, v12, v11, s[0:1]
	v_cndmask_b32_e64 v17, v16, v8, s[6:7]
	s_waitcnt lgkmcnt(1)
	v_cndmask_b32_e64 v15, v14, v9, s[6:7]
	v_cmp_lt_f32_e64 s[8:9], v17, v6
	s_waitcnt lgkmcnt(0)
	s_nop 0
	v_cndmask_b32_e64 v198, v15, v7, s[8:9]
	v_mov_b32_e32 v228, v198
	v_cmp_lt_f32_e32 vcc, v4, v10
	s_nop 1
	v_cndmask_b32_e32 v17, v4, v10, vcc
	v_cndmask_b32_e64 v13, v17, v13, s[0:1]
	v_cndmask_b32_e32 v17, v5, v11, vcc
	v_cndmask_b32_e64 v12, v17, v12, s[0:1]
	v_cmp_lt_f32_e64 s[0:1], v13, v8
	s_nop 1
	v_cndmask_b32_e64 v17, v13, v8, s[0:1]
	v_cndmask_b32_e64 v16, v17, v16, s[6:7]
	v_cndmask_b32_e64 v17, v12, v9, s[0:1]
	v_cndmask_b32_e64 v14, v17, v14, s[6:7]
	v_cmp_lt_f32_e64 s[6:7], v16, v6
	s_nop 1
	v_cndmask_b32_e64 v16, v14, v7, s[6:7]
	v_cndmask_b32_e64 v198, v16, v15, s[8:9]
	v_mov_b32_e32 v230, v198
	v_cmp_lt_f32_e64 s[8:9], v2, v10
	s_nop 1
	v_cndmask_b32_e64 v2, v2, v10, s[8:9]
	v_cndmask_b32_e32 v2, v2, v4, vcc
	v_cndmask_b32_e64 v3, v3, v11, s[8:9]
	v_cndmask_b32_e32 v3, v3, v5, vcc
	v_cmp_lt_f32_e32 vcc, v2, v8
	s_nop 1
	v_cndmask_b32_e32 v2, v2, v8, vcc
	v_cndmask_b32_e64 v2, v2, v13, s[0:1]
	v_cndmask_b32_e32 v3, v3, v9, vcc
	v_cndmask_b32_e64 v3, v3, v12, s[0:1]
	v_cmp_lt_f32_e32 vcc, v2, v6
	s_nop 1
	v_cndmask_b32_e32 v2, v3, v7, vcc
	v_cndmask_b32_e64 v198, v2, v14, s[6:7]
	v_mov_b32_e32 v232, v198
	v_mov_b32_e32 v229, 0
	v_mov_b32_e32 v231, 0
	v_mov_b32_e32 v233, 0
	v_cmp_lt_i32_e64 s[0:1], -1, v228
	v_cmp_lt_i32_e64 s[6:7], -1, v230
	v_cmp_lt_i32_e64 s[8:9], -1, v232
	v_lshlrev_b64 v[8:9], 16, v[228:229]
	v_lshlrev_b64 v[10:11], 16, v[230:231]
	v_lshlrev_b64 v[12:13], 16, v[232:233]
	v_lshl_add_u64 v[2:3], v[228:229], 2, s[16:17]
	v_lshl_add_u64 v[4:5], v[230:231], 2, s[16:17]
	v_lshl_add_u64 v[6:7], v[232:233], 2, s[16:17]
	v_lshl_add_u64 v[8:9], s[20:21], 0, v[8:9]
	v_lshl_add_u64 v[10:11], s[20:21], 0, v[10:11]
	v_lshl_add_u64 v[12:13], s[20:21], 0, v[12:13]
	v_lshlrev_b32_e32 v14, 2, v90
	v_lshl_or_b32 v15, v90, 2, 1
	v_lshl_or_b32 v16, v90, 2, 2
	s_mov_b64 s[40:41], exec
	s_and_b64 exec, s[40:41], s[0:1]
	flat_atomic_add v228, v[2:3], v209 sc0
	s_and_b64 exec, s[40:41], s[6:7]
	flat_atomic_add v230, v[4:5], v209 sc0
	s_and_b64 exec, s[40:41], s[8:9]
	flat_atomic_add v232, v[6:7], v209 sc0
	s_waitcnt vmcnt(0) lgkmcnt(0)
	v_lshl_add_u64 v[12:13], v[232:233], 2, v[12:13]
	flat_store_dword v[12:13], v16
	s_and_b64 exec, s[40:41], s[6:7]
	v_lshl_add_u64 v[10:11], v[230:231], 2, v[10:11]
	flat_store_dword v[10:11], v15
	s_and_b64 exec, s[40:41], s[0:1]
	v_lshl_add_u64 v[8:9], v[228:229], 2, v[8:9]
	flat_store_dword v[8:9], v14
	s_branch .LBB0_714
